# attention loops: every v_pk_add_f32/v_pk_fma_f32 (40 per loop) split into two scalar v_add/v_fma (same per-component rounding); tests guide 7.5 claim that packed f32 beside MFMAs costs more
# speedup vs baseline: 1.0010x; 1.0009x over previous
.LBB0_226:
	v_cvt_f32_i32_e32 v162, v127
	s_lshl_b32 s86, s33, 15
	v_or_b32_e32 v102, s86, v200
	s_waitcnt lgkmcnt(0)
	v_add_f32_e32 v80, 1.0, v162
	v_add_f32_e32 v66, s12, v162
	v_add_f32_e32 v67, s13, v162
	v_add_f32_e32 v68, s16, v162
	v_add_f32_e32 v69, s17, v162
	v_add_f32_e32 v70, s18, v162
	v_add_f32_e32 v71, s19, v162
	v_add_f32_e32 v72, s20, v162
	v_add_f32_e32 v73, s21, v162
	v_add_f32_e32 v74, s22, v162
	v_add_f32_e32 v75, s23, v162
	v_add_f32_e32 v76, s26, v162
	v_add_f32_e32 v77, s27, v162
	v_add_f32_e32 v78, s28, v162
	v_add_f32_e32 v79, s29, v162
	s_barrier
	v_and_b32_e32 v67, 0x7fffffff, v67
	v_and_b32_e32 v66, 0x7fffffff, v66
	v_and_b32_e32 v69, 0x7fffffff, v69
	v_and_b32_e32 v68, 0x7fffffff, v68
	v_and_b32_e32 v71, 0x7fffffff, v71
	v_and_b32_e32 v70, 0x7fffffff, v70
	v_and_b32_e32 v73, 0x7fffffff, v73
	v_and_b32_e32 v72, 0x7fffffff, v72
	v_and_b32_e32 v75, 0x7fffffff, v75
	v_and_b32_e32 v74, 0x7fffffff, v74
	v_and_b32_e32 v77, 0x7fffffff, v77
	v_and_b32_e32 v76, 0x7fffffff, v76
	v_and_b32_e32 v79, 0x7fffffff, v79
	v_and_b32_e32 v78, 0x7fffffff, v78
	v_and_b32_e32 v98, 0x7fffffff, v162
	v_and_b32_e32 v99, 0x7fffffff, v80
	v_mov_b32_e32 v147, v146
	v_add_u32_e32 v129, v102, v202
	v_fma_f32 v80, v120, v78, v146
	v_fma_f32 v81, v121, v79, v147
	v_fma_f32 v78, v118, v76, v146
	v_fma_f32 v79, v119, v77, v147
	v_fma_f32 v76, v116, v74, v146
	v_fma_f32 v77, v117, v75, v147
	v_fma_f32 v74, v114, v72, v146
	v_fma_f32 v75, v115, v73, v147
	v_fma_f32 v72, v112, v70, v146
	v_fma_f32 v73, v113, v71, v147
	v_fma_f32 v70, v110, v68, v146
	v_fma_f32 v71, v111, v69, v147
	v_fma_f32 v68, v108, v66, v146
	v_fma_f32 v69, v109, v67, v147
	v_fma_f32 v66, v106, v98, v148
	v_fma_f32 v67, v107, v99, v149
	ds_read_b128 v[98:101], v129
	v_add_u32_e32 v151, v102, v203
	s_waitcnt vmcnt(3) lgkmcnt(0)
	v_mfma_f32_32x32x16_bf16 v[66:81], v[98:101], v[82:85], v[66:81]
	ds_read_b128 v[98:101], v151
	v_add_u32_e32 v157, v102, v204
	v_add_u32_e32 v161, v102, v205
	s_add_i32 s6, s33, 1
	v_add_u32_e32 v128, 1, v128
	s_cmp_lg_u32 s33, 2
	v_cmp_ge_i32_e32 vcc, v128, v155
	s_waitcnt vmcnt(2) lgkmcnt(0)
	v_mfma_f32_32x32x16_bf16 v[66:81], v[98:101], v[86:89], v[66:81]
	ds_read_b128 v[98:101], v157
	s_cselect_b32 s33, s6, 0
	v_add_u32_e32 v127, 64, v127
	s_or_b64 s[84:85], vcc, s[84:85]
	s_waitcnt vmcnt(1) lgkmcnt(0)
	v_mfma_f32_32x32x16_bf16 v[66:81], v[98:101], v[90:93], v[66:81]
	ds_read_b128 v[98:101], v161
	s_waitcnt vmcnt(0) lgkmcnt(0)
	v_mfma_f32_32x32x16_bf16 v[66:81], v[98:101], v[94:97], v[66:81]
	s_nop 11
	v_exp_f32_e32 v66, v66
	v_exp_f32_e32 v166, v67
	v_exp_f32_e32 v168, v68
	v_exp_f32_e32 v170, v69
	v_add_f32_e32 v132, 0, v66
	v_exp_f32_e32 v188, v78
	v_exp_f32_e32 v212, v79
	v_exp_f32_e32 v214, v80
	v_exp_f32_e32 v216, v81
	v_cvt_pk_bf16_f32 v98, v66, v166
	v_add_f32_e32 v66, s30, v162
	v_add_f32_e32 v67, s31, v162
	v_add_f32_e32 v68, s34, v162
	v_add_f32_e32 v69, s35, v162
	v_add_f32_e32 v78, s64, v162
	v_add_f32_e32 v79, s65, v162
	v_add_f32_e32 v80, s74, v162
	v_add_f32_e32 v81, s75, v162
	v_exp_f32_e32 v172, v70
	v_exp_f32_e32 v174, v71
	v_exp_f32_e32 v176, v72
	v_exp_f32_e32 v178, v73
	v_exp_f32_e32 v180, v74
	v_exp_f32_e32 v182, v75
	v_exp_f32_e32 v184, v76
	v_exp_f32_e32 v186, v77
	v_add_f32_e32 v70, s48, v162
	v_add_f32_e32 v71, s49, v162
	v_add_f32_e32 v72, s54, v162
	v_add_f32_e32 v73, s55, v162
	v_add_f32_e32 v74, s56, v162
	v_add_f32_e32 v75, s57, v162
	v_add_f32_e32 v76, s58, v162
	v_add_f32_e32 v77, s59, v162
	v_and_b32_e32 v163, 0x7fffffff, v81
	v_and_b32_e32 v162, 0x7fffffff, v80
	v_and_b32_e32 v165, 0x7fffffff, v79
	v_and_b32_e32 v164, 0x7fffffff, v78
	v_and_b32_e32 v69, 0x7fffffff, v69
	v_and_b32_e32 v68, 0x7fffffff, v68
	v_and_b32_e32 v67, 0x7fffffff, v67
	v_and_b32_e32 v66, 0x7fffffff, v66
	v_fma_f32 v80, v120, v66, v146
	v_fma_f32 v81, v121, v67, v147
	v_fma_f32 v78, v118, v68, v146
	v_fma_f32 v79, v119, v69, v147
	v_fma_f32 v68, v108, v164, v146
	v_fma_f32 v69, v109, v165, v147
	v_fma_f32 v66, v106, v162, v148
	v_fma_f32 v67, v107, v163, v149
	ds_read_b128 v[162:165], v129 offset:8192
	v_and_b32_e32 v219, 0x7fffffff, v77
	v_and_b32_e32 v218, 0x7fffffff, v76
	v_and_b32_e32 v221, 0x7fffffff, v75
	v_and_b32_e32 v220, 0x7fffffff, v74
	v_and_b32_e32 v73, 0x7fffffff, v73
	v_and_b32_e32 v72, 0x7fffffff, v72
	v_and_b32_e32 v71, 0x7fffffff, v71
	v_and_b32_e32 v70, 0x7fffffff, v70
	v_fma_f32 v76, v116, v70, v146
	v_fma_f32 v77, v117, v71, v147
	v_fma_f32 v74, v114, v72, v146
	v_fma_f32 v75, v115, v73, v147
	v_fma_f32 v72, v112, v220, v146
	v_fma_f32 v73, v113, v221, v147
	v_fma_f32 v70, v110, v218, v146
	v_fma_f32 v71, v111, v219, v147
	v_cvt_pk_bf16_f32 v99, v168, v170
	v_cvt_pk_bf16_f32 v100, v172, v174
	s_waitcnt lgkmcnt(0)
	v_mfma_f32_32x32x16_bf16 v[66:81], v[162:165], v[82:85], v[66:81]
	ds_read_b128 v[162:165], v151 offset:8192
	v_cvt_pk_bf16_f32 v101, v176, v178
	v_cvt_pk_bf16_f32 v102, v180, v182
	v_cvt_pk_bf16_f32 v103, v184, v186
	v_cvt_pk_bf16_f32 v104, v188, v212
	v_cvt_pk_bf16_f32 v105, v214, v216
	s_waitcnt lgkmcnt(0)
	v_mfma_f32_32x32x16_bf16 v[66:81], v[162:165], v[86:89], v[66:81]
	ds_read_b128 v[162:165], v157 offset:8192
	s_waitcnt lgkmcnt(0)
	v_mfma_f32_32x32x16_bf16 v[66:81], v[162:165], v[90:93], v[66:81]
	ds_read_b128 v[162:165], v161 offset:8192
	s_waitcnt lgkmcnt(0)
	s_barrier
	s_waitcnt lgkmcnt(0)
	v_mfma_f32_32x32x16_bf16 v[66:81], v[162:165], v[94:97], v[66:81]
	s_nop 11
	v_exp_f32_e32 v217, v80
	v_or_b32_e32 v80, s86, v193
	v_exp_f32_e32 v161, v81
	v_add_u32_e32 v81, v80, v195
	v_exp_f32_e32 v183, v74
	v_exp_f32_e32 v185, v75
	v_exp_f32_e32 v187, v76
	v_exp_f32_e32 v189, v77
	ds_read_b128 v[74:77], v81 offset:16384
	v_add_u32_e32 v129, v80, v196
	s_waitcnt lgkmcnt(0)
	v_mfma_f32_32x32x16_bf16 v[50:65], v[74:77], v[98:101], v[50:65]
	ds_read_b128 v[74:77], v129 offset:16384
	v_exp_f32_e32 v167, v66
	v_exp_f32_e32 v169, v67
	v_exp_f32_e32 v171, v68
	v_exp_f32_e32 v173, v69
	v_add_f32_e32 v66, v166, v132
	v_add_f32_e32 v67, v167, v133
	v_exp_f32_e32 v175, v70
	s_waitcnt lgkmcnt(0)
	v_mfma_f32_32x32x16_bf16 v[50:65], v[74:77], v[102:105], v[50:65]
	ds_read_b128 v[74:77], v81 offset:20480
	v_add_f32_e64 v66, v168, v66
	v_add_f32_e64 v67, v169, v67
	v_exp_f32_e32 v177, v71
	v_add_f32_e32 v66, v170, v66
	v_add_f32_e32 v67, v171, v67
	v_exp_f32_e32 v179, v72
	v_add_f32_e32 v66, v172, v66
	v_add_f32_e32 v67, v173, v67
	v_exp_f32_e32 v181, v73
	s_waitcnt lgkmcnt(0)
	v_mfma_f32_32x32x16_bf16 v[34:49], v[74:77], v[98:101], v[34:49]
	ds_read_b128 v[74:77], v129 offset:20480
	v_add_f32_e64 v66, v174, v66
	v_add_f32_e64 v67, v175, v67
	v_exp_f32_e32 v213, v78
	v_add_f32_e32 v66, v176, v66
	v_add_f32_e32 v67, v177, v67
	v_exp_f32_e32 v215, v79
	v_add_f32_e32 v66, v178, v66
	v_add_f32_e32 v67, v179, v67
	v_cvt_pk_bf16_f32 v68, v175, v177
	s_waitcnt lgkmcnt(0)
	v_mfma_f32_32x32x16_bf16 v[34:49], v[74:77], v[102:105], v[34:49]
	ds_read_b128 v[74:77], v81 offset:24576
	v_add_f32_e64 v66, v180, v66
	v_add_f32_e64 v67, v181, v67
	v_cvt_pk_bf16_f32 v69, v179, v181
	v_add_f32_e64 v66, v182, v66
	v_add_f32_e64 v67, v183, v67
	v_cvt_pk_bf16_f32 v70, v183, v185
	v_add_f32_e32 v66, v184, v66
	v_add_f32_e32 v67, v185, v67
	v_cvt_pk_bf16_f32 v71, v187, v189
	s_waitcnt lgkmcnt(0)
	v_mfma_f32_32x32x16_bf16 v[18:33], v[74:77], v[98:101], v[18:33]
	ds_read_b128 v[74:77], v129 offset:24576
	v_add_f32_e64 v66, v186, v66
	v_add_f32_e64 v67, v187, v67
	v_cvt_pk_bf16_f32 v72, v213, v215
	v_add_f32_e64 v66, v188, v66
	v_add_f32_e64 v67, v189, v67
	v_cvt_pk_bf16_f32 v73, v217, v161
	v_add_f32_e32 v66, v212, v66
	v_add_f32_e32 v67, v213, v67
	s_waitcnt lgkmcnt(0)
	v_mfma_f32_32x32x16_bf16 v[18:33], v[74:77], v[102:105], v[18:33]
	ds_read_b128 v[74:77], v81 offset:28672
	v_add_u32_e32 v81, v80, v197
	v_add_f32_e64 v66, v214, v66
	v_add_f32_e64 v67, v215, v67
	v_add_u32_e32 v80, v80, v198
	v_add_f32_e32 v66, v216, v66
	v_add_f32_e32 v67, v217, v67
	s_nop 0
	v_add_f32_e32 v78, v160, v66
	v_add_f32_e32 v79, v161, v67
	s_waitcnt lgkmcnt(0)
	v_mfma_f32_32x32x16_bf16 v[2:17], v[74:77], v[98:101], v[2:17]
	ds_read_b128 v[74:77], v129 offset:28672
	v_cvt_pk_bf16_f32 v66, v167, v169
	v_cvt_pk_bf16_f32 v67, v171, v173
	v_add_f32_e32 v160, v78, v79
	s_waitcnt lgkmcnt(0)
	v_mfma_f32_32x32x16_bf16 v[2:17], v[74:77], v[102:105], v[2:17]
	ds_read_b128 v[74:77], v81 offset:16384
	s_waitcnt lgkmcnt(0)
	v_mfma_f32_32x32x16_bf16 v[50:65], v[74:77], v[66:69], v[50:65]
	ds_read_b128 v[74:77], v80 offset:16384
	s_waitcnt lgkmcnt(0)
	v_mfma_f32_32x32x16_bf16 v[50:65], v[74:77], v[70:73], v[50:65]
	ds_read_b128 v[74:77], v81 offset:20480
	s_waitcnt lgkmcnt(0)
	v_mfma_f32_32x32x16_bf16 v[34:49], v[74:77], v[66:69], v[34:49]
	ds_read_b128 v[74:77], v80 offset:20480
	s_waitcnt lgkmcnt(0)
	v_mfma_f32_32x32x16_bf16 v[34:49], v[74:77], v[70:73], v[34:49]
	ds_read_b128 v[74:77], v81 offset:24576
	s_waitcnt lgkmcnt(0)
	v_mfma_f32_32x32x16_bf16 v[18:33], v[74:77], v[66:69], v[18:33]
	ds_read_b128 v[74:77], v80 offset:24576
	s_waitcnt lgkmcnt(0)
	v_mfma_f32_32x32x16_bf16 v[18:33], v[74:77], v[70:73], v[18:33]
	ds_read_b128 v[74:77], v81 offset:28672
	s_waitcnt lgkmcnt(0)
	v_mfma_f32_32x32x16_bf16 v[2:17], v[74:77], v[66:69], v[2:17]
	ds_read_b128 v[66:69], v80 offset:28672
	s_waitcnt lgkmcnt(0)
	v_mfma_f32_32x32x16_bf16 v[2:17], v[66:69], v[70:73], v[2:17]
	s_andn2_b64 exec, exec, s[84:85]
	s_cbranch_execnz .LBB0_226
	s_or_b64 exec, exec, s[84:85]

.LBB0_232:
	s_or_b64 exec, exec, s[86:87]
	v_add_u32_e32 v66, v151, v66
	v_cvt_f32_i32_e32 v212, v66
	s_and_b64 s[6:7], exec, vcc
	s_or_b64 s[84:85], s[6:7], s[84:85]
	s_lshl_b32 s86, s90, 15
	v_or_b32_e32 v102, s86, v200
	v_add_f32_e32 v80, 1.0, v212
	v_add_f32_e32 v66, s12, v212
	v_add_f32_e32 v67, s13, v212
	v_add_f32_e32 v68, s16, v212
	v_add_f32_e32 v69, s17, v212
	v_add_f32_e32 v70, s18, v212
	v_add_f32_e32 v71, s19, v212
	v_add_f32_e32 v72, s20, v212
	v_add_f32_e32 v73, s21, v212
	v_add_f32_e32 v74, s22, v212
	v_add_f32_e32 v75, s23, v212
	v_add_f32_e32 v76, s26, v212
	v_add_f32_e32 v77, s27, v212
	v_add_f32_e32 v78, s28, v212
	v_add_f32_e32 v79, s29, v212
	v_and_b32_e32 v67, 0x7fffffff, v67
	v_and_b32_e32 v66, 0x7fffffff, v66
	v_and_b32_e32 v69, 0x7fffffff, v69
	v_and_b32_e32 v68, 0x7fffffff, v68
	v_and_b32_e32 v71, 0x7fffffff, v71
	v_and_b32_e32 v70, 0x7fffffff, v70
	v_and_b32_e32 v73, 0x7fffffff, v73
	v_and_b32_e32 v72, 0x7fffffff, v72
	v_and_b32_e32 v75, 0x7fffffff, v75
	v_and_b32_e32 v74, 0x7fffffff, v74
	v_and_b32_e32 v77, 0x7fffffff, v77
	v_and_b32_e32 v76, 0x7fffffff, v76
	v_and_b32_e32 v79, 0x7fffffff, v79
	v_and_b32_e32 v78, 0x7fffffff, v78
	v_and_b32_e32 v98, 0x7fffffff, v212
	v_and_b32_e32 v99, 0x7fffffff, v80
	v_mov_b32_e32 v147, v146
	v_add_u32_e32 v127, v102, v202
	v_fma_f32 v80, v124, v78, v146
	v_fma_f32 v81, v125, v79, v147
	v_fma_f32 v78, v122, v76, v146
	v_fma_f32 v79, v123, v77, v147
	v_fma_f32 v76, v120, v74, v146
	v_fma_f32 v77, v121, v75, v147
	v_fma_f32 v74, v118, v72, v146
	v_fma_f32 v75, v119, v73, v147
	v_fma_f32 v72, v116, v70, v146
	v_fma_f32 v73, v117, v71, v147
	v_fma_f32 v70, v114, v68, v146
	v_fma_f32 v71, v115, v69, v147
	v_fma_f32 v68, v112, v66, v146
	v_fma_f32 v69, v113, v67, v147
	v_fma_f32 v66, v110, v98, v148
	v_fma_f32 v67, v111, v99, v149
	ds_read_b128 v[98:101], v127
	v_add_u32_e32 v129, v102, v203
	s_waitcnt lgkmcnt(0)
	v_mfma_f32_32x32x16_bf16 v[66:81], v[98:101], v[82:85], v[66:81]
	ds_read_b128 v[98:101], v129
	v_add_u32_e32 v157, v102, v204
	v_add_u32_e32 v161, v102, v205
	v_add_u32_e32 v141, 1, v141
	s_mov_b32 s90, s33
	s_waitcnt lgkmcnt(0)
	v_mfma_f32_32x32x16_bf16 v[66:81], v[98:101], v[86:89], v[66:81]
	ds_read_b128 v[98:101], v157
	s_waitcnt lgkmcnt(0)
	v_mfma_f32_32x32x16_bf16 v[66:81], v[98:101], v[90:93], v[66:81]
	ds_read_b128 v[98:101], v161
	s_waitcnt lgkmcnt(0)
	v_mfma_f32_32x32x16_bf16 v[66:81], v[98:101], v[94:97], v[66:81]
	s_nop 11
	v_exp_f32_e32 v66, v66
	v_exp_f32_e32 v128, v67
	v_exp_f32_e32 v164, v68
	v_exp_f32_e32 v162, v69
	v_add_f32_e32 v132, 0, v66
	v_exp_f32_e32 v184, v78
	v_exp_f32_e32 v182, v79
	v_exp_f32_e32 v188, v80
	v_exp_f32_e32 v186, v81
	v_cvt_pk_bf16_f32 v102, v66, v128
	v_add_f32_e32 v66, s30, v212
	v_add_f32_e32 v67, s31, v212
	v_add_f32_e32 v68, s34, v212
	v_add_f32_e32 v69, s35, v212
	v_add_f32_e32 v78, s64, v212
	v_add_f32_e32 v79, s65, v212
	v_add_f32_e32 v80, s74, v212
	v_add_f32_e32 v81, s75, v212
	v_exp_f32_e32 v168, v70
	v_exp_f32_e32 v166, v71
	v_exp_f32_e32 v172, v72
	v_exp_f32_e32 v170, v73
	v_exp_f32_e32 v176, v74
	v_exp_f32_e32 v174, v75
	v_exp_f32_e32 v180, v76
	v_exp_f32_e32 v178, v77
	v_add_f32_e32 v70, s48, v212
	v_add_f32_e32 v71, s49, v212
	v_add_f32_e32 v72, s54, v212
	v_add_f32_e32 v73, s55, v212
	v_add_f32_e32 v74, s56, v212
	v_add_f32_e32 v75, s57, v212
	v_add_f32_e32 v76, s58, v212
	v_add_f32_e32 v77, s59, v212
	v_and_b32_e32 v213, 0x7fffffff, v81
	v_and_b32_e32 v212, 0x7fffffff, v80
	v_and_b32_e32 v215, 0x7fffffff, v79
	v_and_b32_e32 v214, 0x7fffffff, v78
	v_and_b32_e32 v69, 0x7fffffff, v69
	v_and_b32_e32 v68, 0x7fffffff, v68
	v_and_b32_e32 v67, 0x7fffffff, v67
	v_and_b32_e32 v66, 0x7fffffff, v66
	v_fma_f32 v80, v124, v66, v146
	v_fma_f32 v81, v125, v67, v147
	v_fma_f32 v78, v122, v68, v146
	v_fma_f32 v79, v123, v69, v147
	v_fma_f32 v68, v112, v214, v146
	v_fma_f32 v69, v113, v215, v147
	v_fma_f32 v66, v110, v212, v148
	v_fma_f32 v67, v111, v213, v149
	ds_read_b128 v[212:215], v127 offset:8192
	v_and_b32_e32 v217, 0x7fffffff, v77
	v_and_b32_e32 v216, 0x7fffffff, v76
	v_and_b32_e32 v219, 0x7fffffff, v75
	v_and_b32_e32 v218, 0x7fffffff, v74
	v_and_b32_e32 v73, 0x7fffffff, v73
	v_and_b32_e32 v72, 0x7fffffff, v72
	v_and_b32_e32 v71, 0x7fffffff, v71
	v_and_b32_e32 v70, 0x7fffffff, v70
	v_fma_f32 v76, v120, v70, v146
	v_fma_f32 v77, v121, v71, v147
	v_fma_f32 v74, v118, v72, v146
	v_fma_f32 v75, v119, v73, v147
	v_fma_f32 v72, v116, v218, v146
	v_fma_f32 v73, v117, v219, v147
	v_fma_f32 v70, v114, v216, v146
	v_fma_f32 v71, v115, v217, v147
	v_cvt_pk_bf16_f32 v103, v164, v162
	v_cvt_pk_bf16_f32 v104, v168, v166
	s_waitcnt lgkmcnt(0)
	v_mfma_f32_32x32x16_bf16 v[66:81], v[212:215], v[82:85], v[66:81]
	ds_read_b128 v[212:215], v129 offset:8192
	v_cvt_pk_bf16_f32 v105, v172, v170
	v_cvt_pk_bf16_f32 v98, v176, v174
	v_cvt_pk_bf16_f32 v99, v180, v178
	v_cvt_pk_bf16_f32 v100, v184, v182
	v_cvt_pk_bf16_f32 v101, v188, v186
	s_waitcnt lgkmcnt(0)
	v_mfma_f32_32x32x16_bf16 v[66:81], v[212:215], v[86:89], v[66:81]
	ds_read_b128 v[212:215], v157 offset:8192
	s_waitcnt lgkmcnt(0)
	v_mfma_f32_32x32x16_bf16 v[66:81], v[212:215], v[90:93], v[66:81]
	ds_read_b128 v[212:215], v161 offset:8192
	s_waitcnt lgkmcnt(0)
	s_barrier
	s_waitcnt lgkmcnt(0)
	v_mfma_f32_32x32x16_bf16 v[66:81], v[212:215], v[94:97], v[66:81]
	s_nop 11
	v_exp_f32_e32 v187, v80
	v_or_b32_e32 v80, s86, v193
	v_exp_f32_e32 v161, v81
	v_add_u32_e32 v81, v80, v195
	v_exp_f32_e32 v179, v76
	v_exp_f32_e32 v185, v77
	v_exp_f32_e32 v183, v78
	v_exp_f32_e32 v189, v79
	ds_read_b128 v[76:79], v81 offset:16384
	v_add_u32_e32 v127, v80, v196
	s_waitcnt lgkmcnt(0)
	v_mfma_f32_32x32x16_bf16 v[50:65], v[76:79], v[102:105], v[50:65]
	ds_read_b128 v[76:79], v127 offset:16384
	v_exp_f32_e32 v129, v66
	v_exp_f32_e32 v165, v67
	v_exp_f32_e32 v163, v68
	v_exp_f32_e32 v169, v69
	v_add_f32_e32 v66, v128, v132
	v_add_f32_e32 v67, v129, v133
	v_exp_f32_e32 v167, v70
	s_waitcnt lgkmcnt(0)
	v_mfma_f32_32x32x16_bf16 v[50:65], v[76:79], v[98:101], v[50:65]
	ds_read_b128 v[76:79], v81 offset:20480
	v_add_f32_e64 v66, v164, v66
	v_add_f32_e64 v67, v165, v67
	v_exp_f32_e32 v173, v71
	v_add_f32_e32 v66, v162, v66
	v_add_f32_e32 v67, v163, v67
	v_exp_f32_e32 v171, v72
	v_exp_f32_e32 v177, v73
	v_add_f32_e32 v66, v168, v66
	v_add_f32_e32 v67, v169, v67
	s_waitcnt lgkmcnt(0)
	v_mfma_f32_32x32x16_bf16 v[34:49], v[76:79], v[102:105], v[34:49]
	ds_read_b128 v[76:79], v127 offset:20480
	v_exp_f32_e32 v175, v74
	v_add_f32_e32 v66, v166, v66
	v_add_f32_e32 v67, v167, v67
	v_exp_f32_e32 v181, v75
	v_add_f32_e32 v66, v172, v66
	v_add_f32_e32 v67, v173, v67
	v_cvt_pk_bf16_f32 v70, v129, v165
	v_add_f32_e32 v66, v170, v66
	v_add_f32_e32 v67, v171, v67
	s_waitcnt lgkmcnt(0)
	v_mfma_f32_32x32x16_bf16 v[34:49], v[76:79], v[98:101], v[34:49]
	ds_read_b128 v[76:79], v81 offset:24576
	v_cvt_pk_bf16_f32 v71, v163, v169
	v_cvt_pk_bf16_f32 v72, v167, v173
	v_cvt_pk_bf16_f32 v73, v171, v177
	v_add_f32_e64 v66, v176, v66
	v_add_f32_e64 v67, v177, v67
	v_cvt_pk_bf16_f32 v68, v183, v189
	v_add_f32_e32 v66, v174, v66
	v_add_f32_e32 v67, v175, v67
	s_waitcnt lgkmcnt(0)
	v_mfma_f32_32x32x16_bf16 v[18:33], v[76:79], v[102:105], v[18:33]
	ds_read_b128 v[76:79], v127 offset:24576
	v_add_f32_e64 v66, v180, v66
	v_add_f32_e64 v67, v181, v67
	v_cvt_pk_bf16_f32 v69, v187, v161
	v_add_f32_e64 v66, v178, v66
	v_add_f32_e64 v67, v179, v67
	v_add_f32_e32 v66, v184, v66
	v_add_f32_e32 v67, v185, v67
	s_waitcnt lgkmcnt(0)
	v_mfma_f32_32x32x16_bf16 v[18:33], v[76:79], v[98:101], v[18:33]
	ds_read_b128 v[76:79], v81 offset:28672
	v_add_u32_e32 v81, v80, v197
	v_add_u32_e32 v80, v80, v198
	v_add_f32_e64 v66, v182, v66
	v_add_f32_e64 v67, v183, v67
	v_add_f32_e32 v66, v188, v66
	v_add_f32_e32 v67, v189, v67
	s_waitcnt lgkmcnt(0)
	v_mfma_f32_32x32x16_bf16 v[2:17], v[76:79], v[102:105], v[2:17]
	ds_read_b128 v[76:79], v127 offset:28672
	v_add_f32_e64 v66, v186, v66
	v_add_f32_e64 v67, v187, v67
	v_add_f32_e64 v74, v160, v66
	v_add_f32_e64 v75, v161, v67
	v_cvt_pk_bf16_f32 v66, v175, v181
	v_cvt_pk_bf16_f32 v67, v179, v185
	v_add_f32_e32 v160, v74, v75
	s_waitcnt lgkmcnt(0)
	v_mfma_f32_32x32x16_bf16 v[2:17], v[76:79], v[98:101], v[2:17]
	ds_read_b128 v[76:79], v81 offset:16384
	s_waitcnt lgkmcnt(0)
	v_mfma_f32_32x32x16_bf16 v[50:65], v[76:79], v[70:73], v[50:65]
	ds_read_b128 v[76:79], v80 offset:16384
	s_waitcnt lgkmcnt(0)
	v_mfma_f32_32x32x16_bf16 v[50:65], v[76:79], v[66:69], v[50:65]
	ds_read_b128 v[76:79], v81 offset:20480
	s_waitcnt lgkmcnt(0)
	v_mfma_f32_32x32x16_bf16 v[34:49], v[76:79], v[70:73], v[34:49]
	ds_read_b128 v[76:79], v80 offset:20480
	s_waitcnt lgkmcnt(0)
	v_mfma_f32_32x32x16_bf16 v[34:49], v[76:79], v[66:69], v[34:49]
	ds_read_b128 v[76:79], v81 offset:24576
	s_waitcnt lgkmcnt(0)
	v_mfma_f32_32x32x16_bf16 v[18:33], v[76:79], v[70:73], v[18:33]
	ds_read_b128 v[76:79], v80 offset:24576
	s_waitcnt lgkmcnt(0)
	v_mfma_f32_32x32x16_bf16 v[18:33], v[76:79], v[66:69], v[18:33]
	ds_read_b128 v[76:79], v81 offset:28672
	s_waitcnt lgkmcnt(0)
	v_mfma_f32_32x32x16_bf16 v[2:17], v[76:79], v[70:73], v[2:17]
	ds_read_b128 v[70:73], v80 offset:28672
	s_waitcnt lgkmcnt(0)
	v_mfma_f32_32x32x16_bf16 v[2:17], v[70:73], v[66:69], v[2:17]
	v_mov_b32_e32 v66, v126
	s_andn2_b64 exec, exec, s[84:85]
	s_cbranch_execz .LBB0_237
